# attention tile loop: waves 4-7 deferred by half a tile with the split right after the running-max step (exp/sum/PV deferred); near-path batching; barrier relay removal; V prefetch
# speedup vs baseline: 1.0240x; 1.0121x over previous
; DEV void attn_tile(LAS unsigned char* lds, const bf16x8 (&qf)[2][2], int tl, int kpos0, int mode, bool near, bool rowsel, const float (&cbias)[2],
;                    unsigned kb, unsigned vb_, unsigned btb, int g4, float (&mrun)[2], float (&lrun)[2], f32x4 (&O)[2][4]) {
;     ...
;     bf16x8 pf[2][2];
; #pragma unroll
;     for (int hh = 0; hh < 2; ++hh) {
;         float lm = fmaxf(fmaxf(sc[hh][0][0], sc[hh][0][1]), fmaxf(sc[hh][0][2], sc[hh][0][3]));
; #pragma unroll
;         for (int kt = 1; kt < 4; ++kt) lm = fmaxf(lm, fmaxf(fmaxf(sc[hh][kt][0], sc[hh][kt][1]), fmaxf(sc[hh][kt][2], sc[hh][kt][3])));
;         const bool inval = mrun[hh] < -1e29f;
;         if (__any(lm > (inval ? -1e29f : 20.f))) {
;             float mx = fmaxf(lm, __shfl_xor(lm, 16)); mx = fmaxf(mx, __shfl_xor(mx, 32));
;             float d = 0.f, alpha = 1.f;
;             if (mx > -1e29f) { d = inval ? mx : fmaxf(mx, 0.f); alpha = inval ? 1.f : __builtin_amdgcn_exp2f(-d); mrun[hh] = inval ? mx : mrun[hh] + d; }
; #pragma unroll
;             for (int kt = 0; kt < 4; ++kt) sc[hh][kt] = sc[hh][kt] - d;
;             lrun[hh] *= alpha;
; #pragma unroll
;             for (int dt = 0; dt < 4; ++dt) O[hh][dt] = O[hh][dt] * alpha;
;         }
.LBB0_275:
	v_max3_f32 v161, v76, v77, v78
	v_max3_f32 v162, v79, v72, v73
	v_max3_f32 v163, v74, v75, v64
	v_max3_f32 v164, v65, v66, v67
	v_max3_f32 v165, v68, v69, v70
	v_max3_f32 v161, v161, v162, v163
	v_max3_f32 v164, v164, v165, v71
	v_max_f32_e32 v161, v161, v164
	v_cndmask_b32_e64 v162, v224, v225, s[42:43]
	v_cmp_gt_f32_e32 vcc, v161, v162
	s_cbranch_vccz .LBB0_277
	ds_bpermute_b32 v162, v143, v161
	v_max_f32_e32 v161, v161, v161
	s_waitcnt lgkmcnt(0)
	v_max_f32_e32 v162, v162, v162
	v_max_f32_e32 v161, v161, v162
	ds_bpermute_b32 v162, v144, v161
	s_waitcnt lgkmcnt(0)
	v_max_f32_e32 v162, v162, v162
	v_max_f32_e32 v161, v161, v162
	v_max_f32_e32 v162, 0, v161
	v_add_f32_e32 v163, v150, v162
	v_cndmask_b32_e64 v162, v162, v161, s[42:43]
	v_exp_f32_e64 v164, -v162
	v_cmp_lt_f32_e32 vcc, s65, v161
	v_cndmask_b32_e64 v163, v163, v161, s[42:43]
	s_nop 0
	v_cndmask_b32_e32 v161, 0, v162, vcc
	v_cndmask_b32_e64 v162, v164, 1.0, s[42:43]
	v_cndmask_b32_e32 v162, 1.0, v162, vcc
	v_cndmask_b32_e32 v150, v150, v163, vcc
	v_sub_f32_e32 v76, v76, v161
	v_sub_f32_e32 v77, v77, v161
	v_sub_f32_e32 v78, v78, v161
	v_sub_f32_e32 v79, v79, v161
	v_sub_f32_e32 v72, v72, v161
	v_sub_f32_e32 v73, v73, v161
	v_sub_f32_e32 v74, v74, v161
	v_sub_f32_e32 v75, v75, v161
	v_sub_f32_e32 v64, v64, v161
	v_sub_f32_e32 v65, v65, v161
	v_sub_f32_e32 v66, v66, v161
	v_sub_f32_e32 v67, v67, v161
	v_sub_f32_e32 v68, v68, v161
	v_sub_f32_e32 v69, v69, v161
	v_sub_f32_e32 v70, v70, v161
	v_sub_f32_e32 v71, v71, v161
	v_mul_f32_e32 v148, v148, v162
	v_pk_mul_f32 v[34:35], v[34:35], v[162:163] op_sel_hi:[1,0]
	v_pk_mul_f32 v[32:33], v[32:33], v[162:163] op_sel_hi:[1,0]
	v_pk_mul_f32 v[42:43], v[42:43], v[162:163] op_sel_hi:[1,0]
	v_pk_mul_f32 v[40:41], v[40:41], v[162:163] op_sel_hi:[1,0]
	v_pk_mul_f32 v[38:39], v[38:39], v[162:163] op_sel_hi:[1,0]
	v_pk_mul_f32 v[36:37], v[36:37], v[162:163] op_sel_hi:[1,0]
	v_pk_mul_f32 v[50:51], v[50:51], v[162:163] op_sel_hi:[1,0]
	v_pk_mul_f32 v[48:49], v[48:49], v[162:163] op_sel_hi:[1,0]

; #define LAS __attribute__((address_space(3)))
; DEV unsigned cvt_pk_bf16(float lo, float hi) { unsigned r; asm volatile("v_cvt_pk_bf16_f32 %0, %1, %2" : "=v"(r) : "v"(lo), "v"(hi)); return r; }
; DEV void attn_tile(LAS unsigned char* lds, const bf16x8 (&qf)[2][2], int tl, int kpos0, int mode, bool near, bool rowsel, const float (&cbias)[2],
;                    unsigned kb, unsigned vb_, unsigned btb, int g4, float (&mrun)[2], float (&lrun)[2], f32x4 (&O)[2][4]) {
;     ...
;         float rs = 0.f;
; #pragma unroll
;         for (int kt = 0; kt < 4; ++kt)
; #pragma unroll
;             for (int r = 0; r < 4; ++r) { const float p = __builtin_amdgcn_exp2f(sc[hh][kt][r]); sc[hh][kt][r] = p; rs += p; }
;         lrun[hh] += rs;
; #pragma unroll
;         for (int kc = 0; kc < 2; ++kc) { u32x4 w; w.x = cvt_pk_bf16(sc[hh][2 * kc][0], sc[hh][2 * kc][1]); w.y = cvt_pk_bf16(sc[hh][2 * kc][2], sc[hh][2 * kc][3]);
;             w.z = cvt_pk_bf16(sc[hh][2 * kc + 1][0], sc[hh][2 * kc + 1][1]); w.w = cvt_pk_bf16(sc[hh][2 * kc + 1][2], sc[hh][2 * kc + 1][3]); pf[hh][kc] = as_bf16x8(w); }
;     }
; #pragma unroll
;     for (int dt = 0; dt < 4; ++dt)
; #pragma unroll
;         for (int kc = 0; kc < 2; ++kc) {
;             const u32x2 va = *(const LAS u32x2*)(lds + vb_ + dt * 2304 + kc * 64);
;             const u32x2 vb = *(const LAS u32x2*)(lds + vb_ + dt * 2304 + kc * 64 + 32);
;             const bf16x8 vf = as_bf16x8((u32x4){va.x, va.y, vb.x, vb.y});
; #pragma unroll
;             for (int hh = 0; hh < 2; ++hh) O[hh][dt] = __builtin_amdgcn_mfma_f32_16x16x32_bf16(vf, pf[hh][kc], O[hh][dt], 0, 0, 0);
;         }
; }
; DEV void attn_item(LAS unsigned char* lds, const bf16_t* P, const bf16_t* QB, const bf16_t* KV, const bf16_t* KC, const bf16_t* VC, const float* rel_bias, bf16_t* OB, int b, int g, int qt) {
;     ...
;             if (mode_n != mode || !more) {
; #pragma unroll
;                 for (int hh = 0; hh < 2; ++hh) { float lt = lrun[hh]; lt += __shfl_xor(lt, 16); lt += __shfl_xor(lt, 32); const float sc = lt > 0.f ? gate[mode][hh] / lt : 0.f;
.Lst_y_entry:
	v_exp_f32_e32 v92, v92
	v_exp_f32_e32 v93, v93
	v_exp_f32_e32 v94, v94
	v_exp_f32_e32 v95, v95
	v_exp_f32_e32 v88, v88
	v_exp_f32_e32 v89, v89
	v_exp_f32_e32 v90, v90
	v_exp_f32_e32 v91, v91
	v_exp_f32_e32 v153, v84
	v_exp_f32_e32 v154, v85
	v_exp_f32_e32 v155, v86
	v_exp_f32_e32 v156, v87
	v_exp_f32_e32 v157, v80
	v_exp_f32_e32 v158, v81
	v_exp_f32_e32 v159, v82
	v_exp_f32_e32 v160, v83
	v_cvt_pk_bf16_f32 v84, v92, v93
	v_cvt_pk_bf16_f32 v85, v94, v95
	v_cvt_pk_bf16_f32 v86, v88, v89
	v_cvt_pk_bf16_f32 v87, v90, v91
	v_cvt_pk_bf16_f32 v80, v153, v154
	v_cvt_pk_bf16_f32 v81, v155, v156
	v_cvt_pk_bf16_f32 v82, v157, v158
	v_cvt_pk_bf16_f32 v83, v159, v160
	v_add_f32_e32 v92, 0, v92
	v_add_f32_e32 v92, v93, v92
	v_add_f32_e32 v92, v94, v92
	v_add_f32_e32 v92, v95, v92
	v_add_f32_e32 v88, v88, v92
	v_add_f32_e32 v88, v89, v88
	v_add_f32_e32 v88, v90, v88
	v_add_f32_e32 v88, v91, v88
	v_add_f32_e32 v88, v153, v88
	v_add_f32_e32 v88, v154, v88
	v_add_f32_e32 v88, v155, v88
	v_add_f32_e32 v88, v156, v88
	v_add_f32_e32 v88, v157, v88
	v_exp_f32_e32 v76, v76
	v_add_f32_e32 v88, v158, v88
	v_exp_f32_e32 v77, v77
	v_add_f32_e32 v88, v159, v88
	v_exp_f32_e32 v78, v78
	v_add_f32_e32 v88, v160, v88
	v_exp_f32_e32 v79, v79
	v_add_f32_e32 v151, v151, v88
	v_add_f32_e32 v88, 0, v76
	v_exp_f32_e32 v72, v72
	v_add_f32_e32 v88, v77, v88
	v_exp_f32_e32 v73, v73
	v_add_f32_e32 v88, v78, v88
	v_exp_f32_e32 v74, v74
	v_add_f32_e32 v88, v79, v88
	v_exp_f32_e32 v75, v75
	v_add_f32_e32 v88, v72, v88
	v_exp_f32_e32 v64, v64
	v_add_f32_e32 v88, v73, v88
	v_exp_f32_e32 v65, v65
	v_add_f32_e32 v88, v74, v88
	v_exp_f32_e32 v66, v66
	v_add_f32_e32 v88, v75, v88
	v_exp_f32_e32 v67, v67
	v_add_f32_e32 v88, v64, v88
	v_exp_f32_e32 v89, v68
	v_add_f32_e32 v88, v65, v88
	v_add_f32_e32 v88, v66, v88
	v_add_f32_e32 v88, v67, v88
	v_add_f32_e32 v68, v89, v88
	v_exp_f32_e32 v88, v69
	v_exp_f32_e32 v90, v70
	v_exp_f32_e32 v91, v71
	v_add_f32_e32 v68, v88, v68
	v_add_f32_e32 v68, v90, v68
	v_add_f32_e32 v68, v91, v68
	v_add_f32_e32 v148, v148, v68
	v_cvt_pk_bf16_f32 v68, v76, v77
	v_cvt_pk_bf16_f32 v69, v78, v79
	v_cvt_pk_bf16_f32 v70, v72, v73
	v_cvt_pk_bf16_f32 v71, v74, v75
	v_cvt_pk_bf16_f32 v64, v64, v65
	v_cvt_pk_bf16_f32 v65, v66, v67
	v_cvt_pk_bf16_f32 v66, v89, v88
	v_cvt_pk_bf16_f32 v67, v90, v91
	s_waitcnt lgkmcnt(7)
	v_mfma_f32_16x16x32_bf16 v[44:47], v[232:235], v[84:87], v[44:47]
	v_mfma_f32_16x16x32_bf16 v[32:35], v[232:235], v[68:71], v[32:35]
	s_waitcnt lgkmcnt(6)
	v_mfma_f32_16x16x32_bf16 v[44:47], v[236:239], v[80:83], v[44:47]
	v_mfma_f32_16x16x32_bf16 v[32:35], v[236:239], v[64:67], v[32:35]
	s_waitcnt lgkmcnt(5)
	v_mfma_f32_16x16x32_bf16 v[56:59], v[240:243], v[84:87], v[56:59]
	v_mfma_f32_16x16x32_bf16 v[40:43], v[240:243], v[68:71], v[40:43]
	s_waitcnt lgkmcnt(4)
	v_mfma_f32_16x16x32_bf16 v[56:59], v[244:247], v[80:83], v[56:59]
	v_mfma_f32_16x16x32_bf16 v[40:43], v[244:247], v[64:67], v[40:43]
	s_waitcnt lgkmcnt(3)
	v_mfma_f32_16x16x32_bf16 v[52:55], v[248:251], v[84:87], v[52:55]
	v_mfma_f32_16x16x32_bf16 v[36:39], v[248:251], v[68:71], v[36:39]
	s_waitcnt lgkmcnt(2)
	v_mfma_f32_16x16x32_bf16 v[52:55], v[198:201], v[80:83], v[52:55]
	v_mfma_f32_16x16x32_bf16 v[36:39], v[198:201], v[64:67], v[36:39]
	s_waitcnt lgkmcnt(1)
	v_mfma_f32_16x16x32_bf16 v[48:51], v[202:205], v[68:71], v[48:51]
	v_mfma_f32_16x16x32_bf16 v[60:63], v[202:205], v[84:87], v[60:63]
	s_waitcnt lgkmcnt(0)
	v_mfma_f32_16x16x32_bf16 v[60:63], v[206:209], v[80:83], v[60:63]
	v_mfma_f32_16x16x32_bf16 v[48:51], v[206:209], v[64:67], v[48:51]
	s_bitcmp1_b32 s101, 8
	s_cbranch_scc0 .LBB0_283
	ds_bpermute_b32 v64, v143, v151
	s_and_b32 s6, s101, 0xff
	s_lshl_b32 s6, s6, 1
	v_mov_b32_e32 v66, 0
	s_waitcnt lgkmcnt(0)
	v_add_f32_e32 v64, v151, v64
	ds_bpermute_b32 v65, v144, v64
	s_waitcnt lgkmcnt(0)
	v_add_f32_e32 v65, v64, v65
	v_mov_b32_e32 v64, 0
	v_cmp_lt_f32_e32 vcc, 0, v65
	s_and_saveexec_b64 s[4:5], vcc
	s_cbranch_execz .LBB0_280
	s_cmp_eq_u32 s6, 1
	s_cselect_b64 vcc, -1, 0
	s_cmp_eq_u32 s6, 2
	v_cndmask_b32_e32 v66, v126, v7, vcc
	s_cselect_b64 vcc, -1, 0
	s_cmp_eq_u32 s6, 3
	v_cndmask_b32_e32 v66, v66, v2, vcc
	s_cselect_b64 vcc, -1, 0
	s_cmp_eq_u32 s6, 4
	v_cndmask_b32_e32 v66, v66, v3, vcc
	s_cselect_b64 vcc, -1, 0
	s_cmp_eq_u32 s6, 5
	v_cndmask_b32_e32 v66, v66, v4, vcc
	s_cselect_b64 vcc, -1, 0
	v_cndmask_b32_e32 v66, v66, v5, vcc
	v_div_scale_f32 v67, s[42:43], v65, v65, v66
	v_rcp_f32_e32 v68, v67
	s_nop 0
	v_fma_f32 v69, -v67, v68, 1.0
	v_fmac_f32_e32 v68, v69, v68
	v_div_scale_f32 v69, vcc, v66, v65, v66
	v_mul_f32_e32 v70, v69, v68
	v_fma_f32 v71, -v67, v70, v69
	v_fmac_f32_e32 v70, v71, v68
	v_fma_f32 v67, -v67, v70, v69
	v_div_fmas_f32 v67, v67, v68, v70
	v_div_fixup_f32 v66, v67, v65, v66
